# per-XCD attention unit queues (K/V-sharing units on one XCD) with work stealing, on top of previous de-serializations
# baseline (speedup 1.0000x reference)
; #define LAS __attribute__((address_space(3)))
; __global__ void __launch_bounds__(NWAVES * 64, 2) hybrid_fwd(Args args) {
;     ...
;         unsigned* qctr = (unsigned*)(ws + WS_CTL) + 3600;
;         volatile LAS unsigned* qslot = (volatile LAS unsigned*)((LAS unsigned char*)lds + MISC_OFF) + 16;
;         if (tid == 0) { const unsigned t_ = __hip_atomic_fetch_add(qctr, 1u, __ATOMIC_RELAXED, __HIP_MEMORY_SCOPE_AGENT); qslot[0] = t_ < 3072u ? (unsigned)ATT_ORDER[t_] : 0xffffffffu; }
.LBB0_675:
	s_cmp_lt_i32 s30, 5
	s_cselect_b64 s[8:9], -1, 0
	s_and_b64 s[0:1], s[8:9], s[2:3]
	s_andn2_b64 vcc, exec, s[0:1]
	s_cbranch_vccnz .LBB0_788
	s_add_u32 s0, s28, 0x3c103840
	s_waitcnt vmcnt(0)
	v_mbcnt_lo_u32_b32 v0, -1, 0
	v_mbcnt_hi_u32_b32 v0, -1, v0
	s_addc_u32 s1, s29, 0
	v_writelane_b32 v254, s0, 44
	v_writelane_b32 v254, s1, 45
	s_nop 1
	v_readlane_b32 s4, v254, 3
	s_nop 3
	s_and_b32 s4, s4, 7
	v_writelane_b32 v254, s4, 42
	v_writelane_b32 v254, s4, 43
	s_mul_i32 s5, s4, 0x300
	s_nop 0
	v_writelane_b32 v254, s5, 41
	s_lshl_b32 s4, s4, 4
	s_add_u32 s0, s0, s4
	s_addc_u32 s1, s1, 0
	v_sub_u32_e32 v0, 0, v0
	v_writelane_b32 v254, s0, 30
	v_cmp_eq_u32_e32 vcc, s11, v0
	s_nop 0
	v_writelane_b32 v254, s1, 31
	s_and_saveexec_b64 s[2:3], vcc
	s_cbranch_execz .LBB0_682
	s_mov_b64 s[6:7], exec
	v_mbcnt_lo_u32_b32 v0, s6, 0
	v_mbcnt_hi_u32_b32 v0, s7, v0
	v_cmp_eq_u32_e32 vcc, 0, v0
	s_and_saveexec_b64 s[4:5], vcc
	s_cbranch_execz .LBB0_679
	s_bcnt1_i32_b64 s0, s[6:7]
	v_mov_b32_e32 v2, s0
	v_readlane_b32 s0, v254, 30
	s_waitcnt lgkmcnt(2)
	v_mov_b32_e32 v1, 0
	v_readlane_b32 s1, v254, 31
	s_nop 4
	global_atomic_add v1, v1, v2, s[0:1] sc0
.LBB0_679:
	s_or_b64 exec, exec, s[4:5]
	s_waitcnt vmcnt(0) lgkmcnt(2)
	v_readfirstlane_b32 s0, v1
	v_mov_b32_e32 v1, -1
	s_nop 0
	v_add_u32_e32 v0, s0, v0
	s_movk_i32 s0, 0x180
	v_cmp_gt_u32_e32 vcc, s0, v0
	s_and_saveexec_b64 s[4:5], vcc
	s_cbranch_execz .LBB0_681
	v_mov_b32_e32 v1, 0
	s_getpc_b64 s[0:1]
	s_add_u32 s0, s0, _ZL9ATT_ORDER@rel32@lo+4
	s_addc_u32 s1, s1, _ZL9ATT_ORDER@rel32@hi+12
	v_readlane_b32 s6, v254, 41
	s_nop 3
	s_add_u32 s0, s0, s6
	s_addc_u32 s1, s1, 0
	v_lshl_add_u64 v[0:1], v[0:1], 1, s[0:1]
	global_load_ushort v1, v[0:1], off

; __global__ void __launch_bounds__(NWAVES * 64, 2) hybrid_fwd(Args args) {
;     ...
;             if (tid == 0) qslot[0] = nxt_ < 3072u ? (unsigned)ATT_ORDER[nxt_] : 0xffffffffu;
.LBB0_784:
	v_mbcnt_lo_u32_b32 v0, -1, 0
	v_mbcnt_hi_u32_b32 v0, -1, v0
	s_nop 0
	v_sub_u32_e32 v0, 0, v0
	v_cmp_eq_u32_e32 vcc, s11, v0
	s_and_saveexec_b64 s[4:5], vcc
	s_cbranch_execz .LBB0_684
	s_mov_b64 s[6:7], 0
	s_movk_i32 s16, 0x180
	v_cmp_gt_u32_e32 vcc, s16, v208
	s_cbranch_vccnz .Lmy_q_have
.Lmy_q_steal:
	v_readlane_b32 s16, v254, 42
	v_readlane_b32 s17, v254, 43
	s_nop 3
	s_add_u32 s16, s16, 1
	s_and_b32 s16, s16, 7
	s_cmp_eq_u32 s16, s17
	s_cbranch_scc1 .Lmy_q_none
	v_writelane_b32 v254, s16, 42
	s_mul_i32 s17, s16, 0x300
	s_nop 0
	v_writelane_b32 v254, s17, 41
	v_readlane_b32 s52, v254, 44
	v_readlane_b32 s53, v254, 45
	s_nop 3
	s_lshl_b32 s16, s16, 4
	s_add_u32 s52, s52, s16
	s_addc_u32 s53, s53, 0
	v_writelane_b32 v254, s52, 30
	v_writelane_b32 v254, s53, 31
	v_mov_b32_e32 v0, 1
	v_mov_b32_e32 v1, 0
	s_nop 4
	global_atomic_add v0, v1, v0, s[52:53] sc0
	s_waitcnt vmcnt(0)
	v_mov_b32_e32 v208, v0
	s_movk_i32 s16, 0x180
	s_nop 0
	v_cmp_gt_u32_e32 vcc, s16, v208
	s_cbranch_vccz .Lmy_q_steal
.Lmy_q_have:
	v_mov_b32_e32 v209, v2
	s_getpc_b64 s[16:17]
	s_add_u32 s16, s16, _ZL9ATT_ORDER@rel32@lo+4
	s_addc_u32 s17, s17, _ZL9ATT_ORDER@rel32@hi+12
	v_readlane_b32 s52, v254, 41
	s_nop 3
	s_add_u32 s16, s16, s52
	s_addc_u32 s17, s17, 0
	v_lshl_add_u64 v[0:1], v[208:209], 1, s[16:17]
	global_load_ushort v0, v[0:1], off
	s_branch .LBB0_683
.Lmy_q_none:
	v_mov_b32_e32 v0, -1
	s_branch .LBB0_683

_ZL9ATT_ORDER:
	.short	32783
	.short	32799
	.short	32815
	.short	32831
	.short	32847
	.short	32863
	.short	32879
	.short	32895
	.short	32782
	.short	32798
	.short	32814
	.short	32830
	.short	32846
	.short	32862
	.short	32878
	.short	32894
	.short	32781
	.short	32797
	.short	32813
	.short	32829
	.short	32845
	.short	32861
	.short	32877
	.short	32893
	.short	32780
	.short	32796
	.short	32812
	.short	32828
	.short	32844
	.short	32860
	.short	32876
	.short	32892
	.short	32779
	.short	32795
	.short	32811
	.short	32827
	.short	32843
	.short	32859
	.short	32875
	.short	32891
	.short	32778
	.short	32794
	.short	32810
	.short	32826
	.short	32842
	.short	32858
	.short	32874
	.short	32890
	.short	863
	.short	895
	.short	2015
	.short	2047
	.short	862
	.short	894
	.short	2014
	.short	2046
	.short	32777
	.short	32793
	.short	32809
	.short	32825
	.short	32841
	.short	32857
	.short	32873
	.short	32889
	.short	861
	.short	893
	.short	2013
	.short	2045
	.short	860
	.short	892
	.short	2012
	.short	2044
	.short	859
	.short	891
	.short	2011
	.short	2043
	.short	32776
	.short	32792
	.short	32808
	.short	32824
	.short	32840
	.short	32856
	.short	32872
	.short	32888
	.short	858
	.short	890
	.short	2010
	.short	2042
	.short	857
	.short	889
	.short	2009
	.short	2041
	.short	856
	.short	888
	.short	2008
	.short	2040
	.short	32775
	.short	32791
	.short	32807
	.short	32823
	.short	32839
	.short	32855
	.short	32871
	.short	32887
	.short	855
	.short	887
	.short	2007
	.short	2039
	.short	854
	.short	886
	.short	2006
	.short	2038
	.short	853
	.short	885
	.short	2005
	.short	2037
	.short	32774
	.short	32790
	.short	32806
	.short	32822
	.short	32838
	.short	32854
	.short	32870
	.short	32886
	.short	852
	.short	884
	.short	2004
	.short	2036
	.short	851
	.short	883
	.short	2003
	.short	2035
	.short	850
	.short	882
	.short	2002
	.short	2034
	.short	32773
	.short	32789
	.short	32805
	.short	32821
	.short	32837
	.short	32853
	.short	32869
	.short	32885
	.short	849
	.short	881
	.short	2001
	.short	2033
	.short	848
	.short	880
	.short	2000
	.short	2032
	.short	847
	.short	879
	.short	1999
	.short	2031
	.short	32772
	.short	32788
	.short	32804
	.short	32820
	.short	32836
	.short	32852
	.short	32868
	.short	32884
	.short	846
	.short	878
	.short	1998
	.short	2030
	.short	845
	.short	877
	.short	1997
	.short	2029
	.short	844
	.short	876
	.short	1996
	.short	2028
	.short	32771
	.short	32787
	.short	32803
	.short	32819
	.short	32835
	.short	32851
	.short	32867
	.short	32883
	.short	843
	.short	875
	.short	1995
	.short	2027
	.short	842
	.short	874
	.short	1994
	.short	2026
	.short	841
	.short	873
	.short	1993
	.short	2025
	.short	32770
	.short	32786
	.short	32802
	.short	32818
	.short	32834
	.short	32850
	.short	32866
	.short	32882
	.short	840
	.short	872
	.short	1992
	.short	2024
	.short	839
	.short	871
	.short	1991
	.short	2023
	.short	1671
	.short	1672
	.short	1673
	.short	1674
	.short	1675
	.short	1676
	.short	1677
	.short	1678
	.short	1679
	.short	1680
	.short	1681
	.short	1682
	.short	1683
	.short	1684
	.short	1685
	.short	1686
	.short	1687
	.short	1688
	.short	1689
	.short	1690
	.short	1691
	.short	1692
	.short	1693
	.short	1694
	.short	1695
	.short	1703
	.short	1704
	.short	1705
	.short	1706
	.short	1707
	.short	1708
	.short	1709
	.short	1710
	.short	1711
	.short	1712
	.short	1713
	.short	1714
	.short	1715
	.short	1716
	.short	1717
	.short	1718
	.short	1719
	.short	1720
	.short	1721
	.short	1722
	.short	1723
	.short	1724
	.short	1725
	.short	1726
	.short	1727
	.short	838
	.short	870
	.short	1670
	.short	1702
	.short	1990
	.short	2022
	.short	32769
	.short	32785
	.short	32801
	.short	32817
	.short	32833
	.short	32849
	.short	32865
	.short	32881
	.short	837
	.short	869
	.short	1669
	.short	1701
	.short	1989
	.short	2021
	.short	836
	.short	868
	.short	1668
	.short	1700
	.short	1988
	.short	2020
	.short	1604
	.short	1605
	.short	1606
	.short	1607
	.short	1608
	.short	1609
	.short	1610
	.short	1611
	.short	1612
	.short	1613
	.short	1614
	.short	1615
	.short	1616
	.short	1617
	.short	1618
	.short	1619
	.short	1620
	.short	1621
	.short	1622
	.short	1623
	.short	1624
	.short	1625
	.short	1626
	.short	1627
	.short	1628
	.short	1629
	.short	1630
	.short	1631
	.short	1636
	.short	1637
	.short	1638
	.short	1639
	.short	1640
	.short	1641
	.short	1642
	.short	1643
	.short	1644
	.short	1645
	.short	1646
	.short	1647
	.short	1648
	.short	1649
	.short	1650
	.short	1651
	.short	1652
	.short	1653
	.short	1654
	.short	1655
	.short	1656
	.short	1657
	.short	1658
	.short	1659
	.short	1660
	.short	1661
	.short	1662
	.short	1663
	.short	835
	.short	867
	.short	1603
	.short	1635
	.short	1667
	.short	1699
	.short	1987
	.short	2019
	.short	32768
	.short	32784
	.short	32800
	.short	32816
	.short	32832
	.short	32848
	.short	32864
	.short	32880
	.short	834
	.short	866
	.short	1602
	.short	1634
	.short	1666
	.short	1698
	.short	1986
	.short	2018
	.short	833
	.short	865
	.short	1601
	.short	1633
	.short	1665
	.short	1697
	.short	1985
	.short	2017
	.short	832
	.short	864
	.short	1600
	.short	1632
	.short	1664
	.short	1696
	.short	1984
	.short	2016
	.short	32911
	.short	32927
	.short	32943
	.short	32959
	.short	32975
	.short	32991
	.short	33007
	.short	33023
	.short	32910
	.short	32926
	.short	32942
	.short	32958
	.short	32974
	.short	32990
	.short	33006
	.short	33022
	.short	32909
	.short	32925
	.short	32941
	.short	32957
	.short	32973
	.short	32989
	.short	33005
	.short	33021
	.short	32908
	.short	32924
	.short	32940
	.short	32956
	.short	32972
	.short	32988
	.short	33004
	.short	33020
	.short	32907
	.short	32923
	.short	32939
	.short	32955
	.short	32971
	.short	32987
	.short	33003
	.short	33019
	.short	32906
	.short	32922
	.short	32938
	.short	32954
	.short	32970
	.short	32986
	.short	33002
	.short	33018
	.short	479
	.short	511
	.short	1951
	.short	1983
	.short	478
	.short	510
	.short	1950
	.short	1982
	.short	32905
	.short	32921
	.short	32937
	.short	32953
	.short	32969
	.short	32985
	.short	33001
	.short	33017
	.short	477
	.short	509
	.short	1949
	.short	1981
	.short	476
	.short	508
	.short	1948
	.short	1980
	.short	475
	.short	507
	.short	1947
	.short	1979
	.short	32904
	.short	32920
	.short	32936
	.short	32952
	.short	32968
	.short	32984
	.short	33000
	.short	33016
	.short	474
	.short	506
	.short	1946
	.short	1978
	.short	473
	.short	505
	.short	1945
	.short	1977
	.short	472
	.short	504
	.short	1944
	.short	1976
	.short	32903
	.short	32919
	.short	32935
	.short	32951
	.short	32967
	.short	32983
	.short	32999
	.short	33015
	.short	471
	.short	503
	.short	1943
	.short	1975
	.short	470
	.short	502
	.short	1942
	.short	1974
	.short	469
	.short	501
	.short	1941
	.short	1973
	.short	32902
	.short	32918
	.short	32934
	.short	32950
	.short	32966
	.short	32982
	.short	32998
	.short	33014
	.short	468
	.short	500
	.short	1940
	.short	1972
	.short	467
	.short	499
	.short	1939
	.short	1971
	.short	466
	.short	498
	.short	1938
	.short	1970
	.short	32901
	.short	32917
	.short	32933
	.short	32949
	.short	32965
	.short	32981
	.short	32997
	.short	33013
	.short	465
	.short	497
	.short	1937
	.short	1969
	.short	464
	.short	496
	.short	1936
	.short	1968
	.short	463
	.short	495
	.short	1935
	.short	1967
	.short	32900
	.short	32916
	.short	32932
	.short	32948
	.short	32964
	.short	32980
	.short	32996
	.short	33012
	.short	462
	.short	494
	.short	1934
	.short	1966
	.short	461
	.short	493
	.short	1933
	.short	1965
	.short	460
	.short	492
	.short	1932
	.short	1964
	.short	32899
	.short	32915
	.short	32931
	.short	32947
	.short	32963
	.short	32979
	.short	32995
	.short	33011
	.short	459
	.short	491
	.short	1931
	.short	1963
	.short	458
	.short	490
	.short	1930
	.short	1962
	.short	457
	.short	489
	.short	1929
	.short	1961
	.short	32898
	.short	32914
	.short	32930
	.short	32946
	.short	32962
	.short	32978
	.short	32994
	.short	33010
	.short	456
	.short	488
	.short	1928
	.short	1960
	.short	455
	.short	487
	.short	1927
	.short	1959
	.short	1159
	.short	1160
	.short	1161
	.short	1162
	.short	1163
	.short	1164
	.short	1165
	.short	1166
	.short	1167
	.short	1168
	.short	1169
	.short	1170
	.short	1171
	.short	1172
	.short	1173
	.short	1174
	.short	1175
	.short	1176
	.short	1177
	.short	1178
	.short	1179
	.short	1180
	.short	1181
	.short	1182
	.short	1183
	.short	1191
	.short	1192
	.short	1193
	.short	1194
	.short	1195
	.short	1196
	.short	1197
	.short	1198
	.short	1199
	.short	1200
	.short	1201
	.short	1202
	.short	1203
	.short	1204
	.short	1205
	.short	1206
	.short	1207
	.short	1208
	.short	1209
	.short	1210
	.short	1211
	.short	1212
	.short	1213
	.short	1214
	.short	1215
	.short	454
	.short	486
	.short	1158
	.short	1190
	.short	1926
	.short	1958
	.short	32897
	.short	32913
	.short	32929
	.short	32945
	.short	32961
	.short	32977
	.short	32993
	.short	33009
	.short	453
	.short	485
	.short	1157
	.short	1189
	.short	1925
	.short	1957
	.short	452
	.short	484
	.short	1156
	.short	1188
	.short	1924
	.short	1956
	.short	1092
	.short	1093
	.short	1094
	.short	1095
	.short	1096
	.short	1097
	.short	1098
	.short	1099
	.short	1100
	.short	1101
	.short	1102
	.short	1103
	.short	1104
	.short	1105
	.short	1106
	.short	1107
	.short	1108
	.short	1109
	.short	1110
	.short	1111
	.short	1112
	.short	1113
	.short	1114
	.short	1115
	.short	1116
	.short	1117
	.short	1118
	.short	1119
	.short	1124
	.short	1125
	.short	1126
	.short	1127
	.short	1128
	.short	1129
	.short	1130
	.short	1131
	.short	1132
	.short	1133
	.short	1134
	.short	1135
	.short	1136
	.short	1137
	.short	1138
	.short	1139
	.short	1140
	.short	1141
	.short	1142
	.short	1143
	.short	1144
	.short	1145
	.short	1146
	.short	1147
	.short	1148
	.short	1149
	.short	1150
	.short	1151
	.short	451
	.short	483
	.short	1091
	.short	1123
	.short	1155
	.short	1187
	.short	1923
	.short	1955
	.short	32896
	.short	32912
	.short	32928
	.short	32944
	.short	32960
	.short	32976
	.short	32992
	.short	33008
	.short	450
	.short	482
	.short	1090
	.short	1122
	.short	1154
	.short	1186
	.short	1922
	.short	1954
	.short	449
	.short	481
	.short	1089
	.short	1121
	.short	1153
	.short	1185
	.short	1921
	.short	1953
	.short	448
	.short	480
	.short	1088
	.short	1120
	.short	1152
	.short	1184
	.short	1920
	.short	1952
	.short	33039
	.short	33055
	.short	33071
	.short	33087
	.short	33103
	.short	33119
	.short	33135
	.short	33151
	.short	33038
	.short	33054
	.short	33070
	.short	33086
	.short	33102
	.short	33118
	.short	33134
	.short	33150
	.short	33037
	.short	33053
	.short	33069
	.short	33085
	.short	33101
	.short	33117
	.short	33133
	.short	33149
	.short	33036
	.short	33052
	.short	33068
	.short	33084
	.short	33100
	.short	33116
	.short	33132
	.short	33148
	.short	33035
	.short	33051
	.short	33067
	.short	33083
	.short	33099
	.short	33115
	.short	33131
	.short	33147
	.short	33034
	.short	33050
	.short	33066
	.short	33082
	.short	33098
	.short	33114
	.short	33130
	.short	33146
	.short	415
	.short	447
	.short	1887
	.short	1919
	.short	414
	.short	446
	.short	1886
	.short	1918
	.short	33033
	.short	33049
	.short	33065
	.short	33081
	.short	33097
	.short	33113
	.short	33129
	.short	33145
	.short	413
	.short	445
	.short	1885
	.short	1917
	.short	412
	.short	444
	.short	1884
	.short	1916
	.short	411
	.short	443
	.short	1883
	.short	1915
	.short	33032
	.short	33048
	.short	33064
	.short	33080
	.short	33096
	.short	33112
	.short	33128
	.short	33144
	.short	410
	.short	442
	.short	1882
	.short	1914
	.short	409
	.short	441
	.short	1881
	.short	1913
	.short	408
	.short	440
	.short	1880
	.short	1912
	.short	33031
	.short	33047
	.short	33063
	.short	33079
	.short	33095
	.short	33111
	.short	33127
	.short	33143
	.short	407
	.short	439
	.short	1879
	.short	1911
	.short	406
	.short	438
	.short	1878
	.short	1910
	.short	405
	.short	437
	.short	1877
	.short	1909
	.short	33030
	.short	33046
	.short	33062
	.short	33078
	.short	33094
	.short	33110
	.short	33126
	.short	33142
	.short	404
	.short	436
	.short	1876
	.short	1908
	.short	403
	.short	435
	.short	1875
	.short	1907
	.short	402
	.short	434
	.short	1874
	.short	1906
	.short	33029
	.short	33045
	.short	33061
	.short	33077
	.short	33093
	.short	33109
	.short	33125
	.short	33141
	.short	401
	.short	433
	.short	1873
	.short	1905
	.short	400
	.short	432
	.short	1872
	.short	1904
	.short	399
	.short	431
	.short	1871
	.short	1903
	.short	33028
	.short	33044
	.short	33060
	.short	33076
	.short	33092
	.short	33108
	.short	33124
	.short	33140
	.short	398
	.short	430
	.short	1870
	.short	1902
	.short	397
	.short	429
	.short	1869
	.short	1901
	.short	396
	.short	428
	.short	1868
	.short	1900
	.short	33027
	.short	33043
	.short	33059
	.short	33075
	.short	33091
	.short	33107
	.short	33123
	.short	33139
	.short	395
	.short	427
	.short	1867
	.short	1899
	.short	394
	.short	426
	.short	1866
	.short	1898
	.short	393
	.short	425
	.short	1865
	.short	1897
	.short	33026
	.short	33042
	.short	33058
	.short	33074
	.short	33090
	.short	33106
	.short	33122
	.short	33138
	.short	392
	.short	424
	.short	1864
	.short	1896
	.short	391
	.short	423
	.short	1863
	.short	1895
	.short	647
	.short	648
	.short	649
	.short	650
	.short	651
	.short	652
	.short	653
	.short	654
	.short	655
	.short	656
	.short	657
	.short	658
	.short	659
	.short	660
	.short	661
	.short	662
	.short	663
	.short	664
	.short	665
	.short	666
	.short	667
	.short	668
	.short	669
	.short	670
	.short	671
	.short	679
	.short	680
	.short	681
	.short	682
	.short	683
	.short	684
	.short	685
	.short	686
	.short	687
	.short	688
	.short	689
	.short	690
	.short	691
	.short	692
	.short	693
	.short	694
	.short	695
	.short	696
	.short	697
	.short	698
	.short	699
	.short	700
	.short	701
	.short	702
	.short	703
	.short	390
	.short	422
	.short	646
	.short	678
	.short	1862
	.short	1894
	.short	33025
	.short	33041
	.short	33057
	.short	33073
	.short	33089
	.short	33105
	.short	33121
	.short	33137
	.short	389
	.short	421
	.short	645
	.short	677
	.short	1861
	.short	1893
	.short	388
	.short	420
	.short	644
	.short	676
	.short	1860
	.short	1892
	.short	580
	.short	581
	.short	582
	.short	583
	.short	584
	.short	585
	.short	586
	.short	587
	.short	588
	.short	589
	.short	590
	.short	591
	.short	592
	.short	593
	.short	594
	.short	595
	.short	596
	.short	597
	.short	598
	.short	599
	.short	600
	.short	601
	.short	602
	.short	603
	.short	604
	.short	605
	.short	606
	.short	607
	.short	612
	.short	613
	.short	614
	.short	615
	.short	616
	.short	617
	.short	618
	.short	619
	.short	620
	.short	621
	.short	622
	.short	623
	.short	624
	.short	625
	.short	626
	.short	627
	.short	628
	.short	629
	.short	630
	.short	631
	.short	632
	.short	633
	.short	634
	.short	635
	.short	636
	.short	637
	.short	638
	.short	639
	.short	387
	.short	419
	.short	579
	.short	611
	.short	643
	.short	675
	.short	1859
	.short	1891
	.short	33024
	.short	33040
	.short	33056
	.short	33072
	.short	33088
	.short	33104
	.short	33120
	.short	33136
	.short	386
	.short	418
	.short	578
	.short	610
	.short	642
	.short	674
	.short	1858
	.short	1890
	.short	385
	.short	417
	.short	577
	.short	609
	.short	641
	.short	673
	.short	1857
	.short	1889
	.short	384
	.short	416
	.short	576
	.short	608
	.short	640
	.short	672
	.short	1856
	.short	1888
	.short	33167
	.short	33183
	.short	33199
	.short	33215
	.short	33231
	.short	33247
	.short	33263
	.short	33279
	.short	33166
	.short	33182
	.short	33198
	.short	33214
	.short	33230
	.short	33246
	.short	33262
	.short	33278
	.short	33165
	.short	33181
	.short	33197
	.short	33213
	.short	33229
	.short	33245
	.short	33261
	.short	33277
	.short	33164
	.short	33180
	.short	33196
	.short	33212
	.short	33228
	.short	33244
	.short	33260
	.short	33276
	.short	33163
	.short	33179
	.short	33195
	.short	33211
	.short	33227
	.short	33243
	.short	33259
	.short	33275
	.short	33162
	.short	33178
	.short	33194
	.short	33210
	.short	33226
	.short	33242
	.short	33258
	.short	33274
	.short	351
	.short	383
	.short	1503
	.short	1535
	.short	350
	.short	382
	.short	1502
	.short	1534
	.short	33161
	.short	33177
	.short	33193
	.short	33209
	.short	33225
	.short	33241
	.short	33257
	.short	33273
	.short	349
	.short	381
	.short	1501
	.short	1533
	.short	348
	.short	380
	.short	1500
	.short	1532
	.short	347
	.short	379
	.short	1499
	.short	1531
	.short	33160
	.short	33176
	.short	33192
	.short	33208
	.short	33224
	.short	33240
	.short	33256
	.short	33272
	.short	346
	.short	378
	.short	1498
	.short	1530
	.short	345
	.short	377
	.short	1497
	.short	1529
	.short	344
	.short	376
	.short	1496
	.short	1528
	.short	33159
	.short	33175
	.short	33191
	.short	33207
	.short	33223
	.short	33239
	.short	33255
	.short	33271
	.short	343
	.short	375
	.short	1495
	.short	1527
	.short	342
	.short	374
	.short	1494
	.short	1526
	.short	341
	.short	373
	.short	1493
	.short	1525
	.short	33158
	.short	33174
	.short	33190
	.short	33206
	.short	33222
	.short	33238
	.short	33254
	.short	33270
	.short	340
	.short	372
	.short	1492
	.short	1524
	.short	339
	.short	371
	.short	1491
	.short	1523
	.short	338
	.short	370
	.short	1490
	.short	1522
	.short	33157
	.short	33173
	.short	33189
	.short	33205
	.short	33221
	.short	33237
	.short	33253
	.short	33269
	.short	337
	.short	369
	.short	1489
	.short	1521
	.short	336
	.short	368
	.short	1488
	.short	1520
	.short	335
	.short	367
	.short	1487
	.short	1519
	.short	33156
	.short	33172
	.short	33188
	.short	33204
	.short	33220
	.short	33236
	.short	33252
	.short	33268
	.short	334
	.short	366
	.short	1486
	.short	1518
	.short	333
	.short	365
	.short	1485
	.short	1517
	.short	332
	.short	364
	.short	1484
	.short	1516
	.short	33155
	.short	33171
	.short	33187
	.short	33203
	.short	33219
	.short	33235
	.short	33251
	.short	33267
	.short	331
	.short	363
	.short	1483
	.short	1515
	.short	330
	.short	362
	.short	1482
	.short	1514
	.short	329
	.short	361
	.short	1481
	.short	1513
	.short	33154
	.short	33170
	.short	33186
	.short	33202
	.short	33218
	.short	33234
	.short	33250
	.short	33266
	.short	328
	.short	360
	.short	1480
	.short	1512
	.short	327
	.short	359
	.short	1479
	.short	1511
	.short	135
	.short	136
	.short	137
	.short	138
	.short	139
	.short	140
	.short	141
	.short	142
	.short	143
	.short	144
	.short	145
	.short	146
	.short	147
	.short	148
	.short	149
	.short	150
	.short	151
	.short	152
	.short	153
	.short	154
	.short	155
	.short	156
	.short	157
	.short	158
	.short	159
	.short	167
	.short	168
	.short	169
	.short	170
	.short	171
	.short	172
	.short	173
	.short	174
	.short	175
	.short	176
	.short	177
	.short	178
	.short	179
	.short	180
	.short	181
	.short	182
	.short	183
	.short	184
	.short	185
	.short	186
	.short	187
	.short	188
	.short	189
	.short	190
	.short	191
	.short	134
	.short	166
	.short	326
	.short	358
	.short	1478
	.short	1510
	.short	33153
	.short	33169
	.short	33185
	.short	33201
	.short	33217
	.short	33233
	.short	33249
	.short	33265
	.short	133
	.short	165
	.short	325
	.short	357
	.short	1477
	.short	1509
	.short	132
	.short	164
	.short	324
	.short	356
	.short	1476
	.short	1508
	.short	68
	.short	69
	.short	70
	.short	71
	.short	72
	.short	73
	.short	74
	.short	75
	.short	76
	.short	77
	.short	78
	.short	79
	.short	80
	.short	81
	.short	82
	.short	83
	.short	84
	.short	85
	.short	86
	.short	87
	.short	88
	.short	89
	.short	90
	.short	91
	.short	92
	.short	93
	.short	94
	.short	95
	.short	100
	.short	101
	.short	102
	.short	103
	.short	104
	.short	105
	.short	106
	.short	107
	.short	108
	.short	109
	.short	110
	.short	111
	.short	112
	.short	113
	.short	114
	.short	115
	.short	116
	.short	117
	.short	118
	.short	119
	.short	120
	.short	121
	.short	122
	.short	123
	.short	124
	.short	125
	.short	126
	.short	127
	.short	67
	.short	99
	.short	131
	.short	163
	.short	323
	.short	355
	.short	1475
	.short	1507
	.short	33152
	.short	33168
	.short	33184
	.short	33200
	.short	33216
	.short	33232
	.short	33248
	.short	33264
	.short	66
	.short	98
	.short	130
	.short	162
	.short	322
	.short	354
	.short	1474
	.short	1506
	.short	65
	.short	97
	.short	129
	.short	161
	.short	321
	.short	353
	.short	1473
	.short	1505
	.short	64
	.short	96
	.short	128
	.short	160
	.short	320
	.short	352
	.short	1472
	.short	1504
	.short	33295
	.short	33311
	.short	33327
	.short	33343
	.short	33359
	.short	33375
	.short	33391
	.short	33407
	.short	33294
	.short	33310
	.short	33326
	.short	33342
	.short	33358
	.short	33374
	.short	33390
	.short	33406
	.short	33293
	.short	33309
	.short	33325
	.short	33341
	.short	33357
	.short	33373
	.short	33389
	.short	33405
	.short	33292
	.short	33308
	.short	33324
	.short	33340
	.short	33356
	.short	33372
	.short	33388
	.short	33404
	.short	33291
	.short	33307
	.short	33323
	.short	33339
	.short	33355
	.short	33371
	.short	33387
	.short	33403
	.short	33290
	.short	33306
	.short	33322
	.short	33338
	.short	33354
	.short	33370
	.short	33386
	.short	33402
	.short	1439
	.short	1471
	.short	1438
	.short	1470
	.short	33289
	.short	33305
	.short	33321
	.short	33337
	.short	33353
	.short	33369
	.short	33385
	.short	33401
	.short	1437
	.short	1469
	.short	1821
	.short	1822
	.short	1823
	.short	1853
	.short	1854
	.short	1855
	.short	1436
	.short	1468
	.short	1820
	.short	1852
	.short	1435
	.short	1467
	.short	1819
	.short	1851
	.short	33288
	.short	33304
	.short	33320
	.short	33336
	.short	33352
	.short	33368
	.short	33384
	.short	33400
	.short	1434
	.short	1466
	.short	1818
	.short	1850
	.short	1433
	.short	1465
	.short	1817
	.short	1849
	.short	1432
	.short	1464
	.short	1816
	.short	1848
	.short	33287
	.short	33303
	.short	33319
	.short	33335
	.short	33351
	.short	33367
	.short	33383
	.short	33399
	.short	1431
	.short	1463
	.short	1815
	.short	1847
	.short	1430
	.short	1462
	.short	1814
	.short	1846
	.short	1429
	.short	1461
	.short	1813
	.short	1845
	.short	33286
	.short	33302
	.short	33318
	.short	33334
	.short	33350
	.short	33366
	.short	33382
	.short	33398
	.short	1428
	.short	1460
	.short	1812
	.short	1844
	.short	1427
	.short	1459
	.short	1811
	.short	1843
	.short	1426
	.short	1458
	.short	1810
	.short	1842
	.short	33285
	.short	33301
	.short	33317
	.short	33333
	.short	33349
	.short	33365
	.short	33381
	.short	33397
	.short	1425
	.short	1457
	.short	1809
	.short	1841
	.short	1424
	.short	1456
	.short	1808
	.short	1840
	.short	1423
	.short	1455
	.short	1807
	.short	1839
	.short	33284
	.short	33300
	.short	33316
	.short	33332
	.short	33348
	.short	33364
	.short	33380
	.short	33396
	.short	1422
	.short	1454
	.short	1806
	.short	1838
	.short	1742
	.short	1743
	.short	1744
	.short	1745
	.short	1746
	.short	1747
	.short	1748
	.short	1749
	.short	1750
	.short	1751
	.short	1752
	.short	1753
	.short	1754
	.short	1755
	.short	1756
	.short	1757
	.short	1758
	.short	1759
	.short	1774
	.short	1775
	.short	1776
	.short	1777
	.short	1778
	.short	1779
	.short	1780
	.short	1781
	.short	1782
	.short	1783
	.short	1784
	.short	1785
	.short	1786
	.short	1787
	.short	1788
	.short	1789
	.short	1790
	.short	1791
	.short	1421
	.short	1453
	.short	1741
	.short	1773
	.short	1805
	.short	1837
	.short	1420
	.short	1452
	.short	1740
	.short	1772
	.short	1804
	.short	1836
	.short	33283
	.short	33299
	.short	33315
	.short	33331
	.short	33347
	.short	33363
	.short	33379
	.short	33395
	.short	1419
	.short	1451
	.short	1739
	.short	1771
	.short	1803
	.short	1835
	.short	1418
	.short	1450
	.short	1738
	.short	1770
	.short	1802
	.short	1834
	.short	1417
	.short	1449
	.short	1737
	.short	1769
	.short	1801
	.short	1833
	.short	33282
	.short	33298
	.short	33314
	.short	33330
	.short	33346
	.short	33362
	.short	33378
	.short	33394
	.short	1416
	.short	1448
	.short	1736
	.short	1768
	.short	1800
	.short	1832
	.short	1415
	.short	1447
	.short	1735
	.short	1767
	.short	1799
	.short	1831
	.short	1414
	.short	1446
	.short	1734
	.short	1766
	.short	1798
	.short	1830
	.short	33281
	.short	33297
	.short	33313
	.short	33329
	.short	33345
	.short	33361
	.short	33377
	.short	33393
	.short	1413
	.short	1445
	.short	1733
	.short	1765
	.short	1797
	.short	1829
	.short	1412
	.short	1444
	.short	1732
	.short	1764
	.short	1796
	.short	1828
	.short	1411
	.short	1443
	.short	1731
	.short	1763
	.short	1795
	.short	1827
	.short	33280
	.short	33296
	.short	33312
	.short	33328
	.short	33344
	.short	33360
	.short	33376
	.short	33392
	.short	1410
	.short	1442
	.short	1730
	.short	1762
	.short	1794
	.short	1826
	.short	1538
	.short	1539
	.short	1540
	.short	1541
	.short	1542
	.short	1543
	.short	1544
	.short	1545
	.short	1546
	.short	1547
	.short	1548
	.short	1549
	.short	1550
	.short	1551
	.short	1552
	.short	1553
	.short	1554
	.short	1555
	.short	1556
	.short	1557
	.short	1558
	.short	1559
	.short	1560
	.short	1561
	.short	1562
	.short	1563
	.short	1564
	.short	1565
	.short	1566
	.short	1567
	.short	1570
	.short	1571
	.short	1572
	.short	1573
	.short	1574
	.short	1575
	.short	1576
	.short	1577
	.short	1578
	.short	1579
	.short	1580
	.short	1581
	.short	1582
	.short	1583
	.short	1584
	.short	1585
	.short	1586
	.short	1587
	.short	1588
	.short	1589
	.short	1590
	.short	1591
	.short	1592
	.short	1593
	.short	1594
	.short	1595
	.short	1596
	.short	1597
	.short	1598
	.short	1599
	.short	1409
	.short	1441
	.short	1537
	.short	1569
	.short	1729
	.short	1761
	.short	1793
	.short	1825
	.short	1408
	.short	1440
	.short	1536
	.short	1568
	.short	1728
	.short	1760
	.short	1792
	.short	1824
	.short	33423
	.short	33439
	.short	33455
	.short	33471
	.short	33487
	.short	33503
	.short	33519
	.short	33535
	.short	33422
	.short	33438
	.short	33454
	.short	33470
	.short	33486
	.short	33502
	.short	33518
	.short	33534
	.short	33421
	.short	33437
	.short	33453
	.short	33469
	.short	33485
	.short	33501
	.short	33517
	.short	33533
	.short	33420
	.short	33436
	.short	33452
	.short	33468
	.short	33484
	.short	33500
	.short	33516
	.short	33532
	.short	33419
	.short	33435
	.short	33451
	.short	33467
	.short	33483
	.short	33499
	.short	33515
	.short	33531
	.short	33418
	.short	33434
	.short	33450
	.short	33466
	.short	33482
	.short	33498
	.short	33514
	.short	33530
	.short	1375
	.short	1407
	.short	1374
	.short	1406
	.short	33417
	.short	33433
	.short	33449
	.short	33465
	.short	33481
	.short	33497
	.short	33513
	.short	33529
	.short	1373
	.short	1405
	.short	1309
	.short	1310
	.short	1311
	.short	1341
	.short	1342
	.short	1343
	.short	1308
	.short	1340
	.short	1372
	.short	1404
	.short	1307
	.short	1339
	.short	1371
	.short	1403
	.short	33416
	.short	33432
	.short	33448
	.short	33464
	.short	33480
	.short	33496
	.short	33512
	.short	33528
	.short	1306
	.short	1338
	.short	1370
	.short	1402
	.short	1305
	.short	1337
	.short	1369
	.short	1401
	.short	1304
	.short	1336
	.short	1368
	.short	1400
	.short	33415
	.short	33431
	.short	33447
	.short	33463
	.short	33479
	.short	33495
	.short	33511
	.short	33527
	.short	1303
	.short	1335
	.short	1367
	.short	1399
	.short	1302
	.short	1334
	.short	1366
	.short	1398
	.short	1301
	.short	1333
	.short	1365
	.short	1397
	.short	33414
	.short	33430
	.short	33446
	.short	33462
	.short	33478
	.short	33494
	.short	33510
	.short	33526
	.short	1300
	.short	1332
	.short	1364
	.short	1396
	.short	1299
	.short	1331
	.short	1363
	.short	1395
	.short	1298
	.short	1330
	.short	1362
	.short	1394
	.short	33413
	.short	33429
	.short	33445
	.short	33461
	.short	33477
	.short	33493
	.short	33509
	.short	33525
	.short	1297
	.short	1329
	.short	1361
	.short	1393
	.short	1296
	.short	1328
	.short	1360
	.short	1392
	.short	1295
	.short	1327
	.short	1359
	.short	1391
	.short	33412
	.short	33428
	.short	33444
	.short	33460
	.short	33476
	.short	33492
	.short	33508
	.short	33524
	.short	1294
	.short	1326
	.short	1358
	.short	1390
	.short	1230
	.short	1231
	.short	1232
	.short	1233
	.short	1234
	.short	1235
	.short	1236
	.short	1237
	.short	1238
	.short	1239
	.short	1240
	.short	1241
	.short	1242
	.short	1243
	.short	1244
	.short	1245
	.short	1246
	.short	1247
	.short	1262
	.short	1263
	.short	1264
	.short	1265
	.short	1266
	.short	1267
	.short	1268
	.short	1269
	.short	1270
	.short	1271
	.short	1272
	.short	1273
	.short	1274
	.short	1275
	.short	1276
	.short	1277
	.short	1278
	.short	1279
	.short	1229
	.short	1261
	.short	1293
	.short	1325
	.short	1357
	.short	1389
	.short	1228
	.short	1260
	.short	1292
	.short	1324
	.short	1356
	.short	1388
	.short	33411
	.short	33427
	.short	33443
	.short	33459
	.short	33475
	.short	33491
	.short	33507
	.short	33523
	.short	1227
	.short	1259
	.short	1291
	.short	1323
	.short	1355
	.short	1387
	.short	1226
	.short	1258
	.short	1290
	.short	1322
	.short	1354
	.short	1386
	.short	1225
	.short	1257
	.short	1289
	.short	1321
	.short	1353
	.short	1385
	.short	33410
	.short	33426
	.short	33442
	.short	33458
	.short	33474
	.short	33490
	.short	33506
	.short	33522
	.short	1224
	.short	1256
	.short	1288
	.short	1320
	.short	1352
	.short	1384
	.short	1223
	.short	1255
	.short	1287
	.short	1319
	.short	1351
	.short	1383
	.short	1222
	.short	1254
	.short	1286
	.short	1318
	.short	1350
	.short	1382
	.short	33409
	.short	33425
	.short	33441
	.short	33457
	.short	33473
	.short	33489
	.short	33505
	.short	33521
	.short	1221
	.short	1253
	.short	1285
	.short	1317
	.short	1349
	.short	1381
	.short	1220
	.short	1252
	.short	1284
	.short	1316
	.short	1348
	.short	1380
	.short	1219
	.short	1251
	.short	1283
	.short	1315
	.short	1347
	.short	1379
	.short	33408
	.short	33424
	.short	33440
	.short	33456
	.short	33472
	.short	33488
	.short	33504
	.short	33520
	.short	1218
	.short	1250
	.short	1282
	.short	1314
	.short	1346
	.short	1378
	.short	1026
	.short	1027
	.short	1028
	.short	1029
	.short	1030
	.short	1031
	.short	1032
	.short	1033
	.short	1034
	.short	1035
	.short	1036
	.short	1037
	.short	1038
	.short	1039
	.short	1040
	.short	1041
	.short	1042
	.short	1043
	.short	1044
	.short	1045
	.short	1046
	.short	1047
	.short	1048
	.short	1049
	.short	1050
	.short	1051
	.short	1052
	.short	1053
	.short	1054
	.short	1055
	.short	1058
	.short	1059
	.short	1060
	.short	1061
	.short	1062
	.short	1063
	.short	1064
	.short	1065
	.short	1066
	.short	1067
	.short	1068
	.short	1069
	.short	1070
	.short	1071
	.short	1072
	.short	1073
	.short	1074
	.short	1075
	.short	1076
	.short	1077
	.short	1078
	.short	1079
	.short	1080
	.short	1081
	.short	1082
	.short	1083
	.short	1084
	.short	1085
	.short	1086
	.short	1087
	.short	1025
	.short	1057
	.short	1217
	.short	1249
	.short	1281
	.short	1313
	.short	1345
	.short	1377
	.short	1024
	.short	1056
	.short	1216
	.short	1248
	.short	1280
	.short	1312
	.short	1344
	.short	1376
	.short	33551
	.short	33567
	.short	33583
	.short	33599
	.short	33615
	.short	33631
	.short	33647
	.short	33663
	.short	33550
	.short	33566
	.short	33582
	.short	33598
	.short	33614
	.short	33630
	.short	33646
	.short	33662
	.short	33549
	.short	33565
	.short	33581
	.short	33597
	.short	33613
	.short	33629
	.short	33645
	.short	33661
	.short	33548
	.short	33564
	.short	33580
	.short	33596
	.short	33612
	.short	33628
	.short	33644
	.short	33660
	.short	33547
	.short	33563
	.short	33579
	.short	33595
	.short	33611
	.short	33627
	.short	33643
	.short	33659
	.short	33546
	.short	33562
	.short	33578
	.short	33594
	.short	33610
	.short	33626
	.short	33642
	.short	33658
	.short	991
	.short	1023
	.short	990
	.short	1022
	.short	33545
	.short	33561
	.short	33577
	.short	33593
	.short	33609
	.short	33625
	.short	33641
	.short	33657
	.short	989
	.short	1021
	.short	797
	.short	798
	.short	799
	.short	829
	.short	830
	.short	831
	.short	796
	.short	828
	.short	988
	.short	1020
	.short	795
	.short	827
	.short	987
	.short	1019
	.short	33544
	.short	33560
	.short	33576
	.short	33592
	.short	33608
	.short	33624
	.short	33640
	.short	33656
	.short	794
	.short	826
	.short	986
	.short	1018
	.short	793
	.short	825
	.short	985
	.short	1017
	.short	792
	.short	824
	.short	984
	.short	1016
	.short	33543
	.short	33559
	.short	33575
	.short	33591
	.short	33607
	.short	33623
	.short	33639
	.short	33655
	.short	791
	.short	823
	.short	983
	.short	1015
	.short	790
	.short	822
	.short	982
	.short	1014
	.short	789
	.short	821
	.short	981
	.short	1013
	.short	33542
	.short	33558
	.short	33574
	.short	33590
	.short	33606
	.short	33622
	.short	33638
	.short	33654
	.short	788
	.short	820
	.short	980
	.short	1012
	.short	787
	.short	819
	.short	979
	.short	1011
	.short	786
	.short	818
	.short	978
	.short	1010
	.short	33541
	.short	33557
	.short	33573
	.short	33589
	.short	33605
	.short	33621
	.short	33637
	.short	33653
	.short	785
	.short	817
	.short	977
	.short	1009
	.short	784
	.short	816
	.short	976
	.short	1008
	.short	783
	.short	815
	.short	975
	.short	1007
	.short	33540
	.short	33556
	.short	33572
	.short	33588
	.short	33604
	.short	33620
	.short	33636
	.short	33652
	.short	782
	.short	814
	.short	974
	.short	1006
	.short	718
	.short	719
	.short	720
	.short	721
	.short	722
	.short	723
	.short	724
	.short	725
	.short	726
	.short	727
	.short	728
	.short	729
	.short	730
	.short	731
	.short	732
	.short	733
	.short	734
	.short	735
	.short	750
	.short	751
	.short	752
	.short	753
	.short	754
	.short	755
	.short	756
	.short	757
	.short	758
	.short	759
	.short	760
	.short	761
	.short	762
	.short	763
	.short	764
	.short	765
	.short	766
	.short	767
	.short	717
	.short	749
	.short	781
	.short	813
	.short	973
	.short	1005
	.short	716
	.short	748
	.short	780
	.short	812
	.short	972
	.short	1004
	.short	33539
	.short	33555
	.short	33571
	.short	33587
	.short	33603
	.short	33619
	.short	33635
	.short	33651
	.short	715
	.short	747
	.short	779
	.short	811
	.short	971
	.short	1003
	.short	714
	.short	746
	.short	778
	.short	810
	.short	970
	.short	1002
	.short	713
	.short	745
	.short	777
	.short	809
	.short	969
	.short	1001
	.short	33538
	.short	33554
	.short	33570
	.short	33586
	.short	33602
	.short	33618
	.short	33634
	.short	33650
	.short	712
	.short	744
	.short	776
	.short	808
	.short	968
	.short	1000
	.short	711
	.short	743
	.short	775
	.short	807
	.short	967
	.short	999
	.short	710
	.short	742
	.short	774
	.short	806
	.short	966
	.short	998
	.short	33537
	.short	33553
	.short	33569
	.short	33585
	.short	33601
	.short	33617
	.short	33633
	.short	33649
	.short	709
	.short	741
	.short	773
	.short	805
	.short	965
	.short	997
	.short	708
	.short	740
	.short	772
	.short	804
	.short	964
	.short	996
	.short	707
	.short	739
	.short	771
	.short	803
	.short	963
	.short	995
	.short	33536
	.short	33552
	.short	33568
	.short	33584
	.short	33600
	.short	33616
	.short	33632
	.short	33648
	.short	706
	.short	738
	.short	770
	.short	802
	.short	962
	.short	994
	.short	514
	.short	515
	.short	516
	.short	517
	.short	518
	.short	519
	.short	520
	.short	521
	.short	522
	.short	523
	.short	524
	.short	525
	.short	526
	.short	527
	.short	528
	.short	529
	.short	530
	.short	531
	.short	532
	.short	533
	.short	534
	.short	535
	.short	536
	.short	537
	.short	538
	.short	539
	.short	540
	.short	541
	.short	542
	.short	543
	.short	546
	.short	547
	.short	548
	.short	549
	.short	550
	.short	551
	.short	552
	.short	553
	.short	554
	.short	555
	.short	556
	.short	557
	.short	558
	.short	559
	.short	560
	.short	561
	.short	562
	.short	563
	.short	564
	.short	565
	.short	566
	.short	567
	.short	568
	.short	569
	.short	570
	.short	571
	.short	572
	.short	573
	.short	574
	.short	575
	.short	513
	.short	545
	.short	705
	.short	737
	.short	769
	.short	801
	.short	961
	.short	993
	.short	512
	.short	544
	.short	704
	.short	736
	.short	768
	.short	800
	.short	960
	.short	992
	.short	33679
	.short	33695
	.short	33711
	.short	33727
	.short	33743
	.short	33759
	.short	33775
	.short	33791
	.short	33678
	.short	33694
	.short	33710
	.short	33726
	.short	33742
	.short	33758
	.short	33774
	.short	33790
	.short	33677
	.short	33693
	.short	33709
	.short	33725
	.short	33741
	.short	33757
	.short	33773
	.short	33789
	.short	33676
	.short	33692
	.short	33708
	.short	33724
	.short	33740
	.short	33756
	.short	33772
	.short	33788
	.short	33675
	.short	33691
	.short	33707
	.short	33723
	.short	33739
	.short	33755
	.short	33771
	.short	33787
	.short	33674
	.short	33690
	.short	33706
	.short	33722
	.short	33738
	.short	33754
	.short	33770
	.short	33786
	.short	927
	.short	959
	.short	926
	.short	958
	.short	33673
	.short	33689
	.short	33705
	.short	33721
	.short	33737
	.short	33753
	.short	33769
	.short	33785
	.short	925
	.short	957
	.short	285
	.short	286
	.short	287
	.short	317
	.short	318
	.short	319
	.short	284
	.short	316
	.short	924
	.short	956
	.short	283
	.short	315
	.short	923
	.short	955
	.short	33672
	.short	33688
	.short	33704
	.short	33720
	.short	33736
	.short	33752
	.short	33768
	.short	33784
	.short	282
	.short	314
	.short	922
	.short	954
	.short	281
	.short	313
	.short	921
	.short	953
	.short	280
	.short	312
	.short	920
	.short	952
	.short	33671
	.short	33687
	.short	33703
	.short	33719
	.short	33735
	.short	33751
	.short	33767
	.short	33783
	.short	279
	.short	311
	.short	919
	.short	951
	.short	278
	.short	310
	.short	918
	.short	950
	.short	277
	.short	309
	.short	917
	.short	949
	.short	33670
	.short	33686
	.short	33702
	.short	33718
	.short	33734
	.short	33750
	.short	33766
	.short	33782
	.short	276
	.short	308
	.short	916
	.short	948
	.short	275
	.short	307
	.short	915
	.short	947
	.short	274
	.short	306
	.short	914
	.short	946
	.short	33669
	.short	33685
	.short	33701
	.short	33717
	.short	33733
	.short	33749
	.short	33765
	.short	33781
	.short	273
	.short	305
	.short	913
	.short	945
	.short	272
	.short	304
	.short	912
	.short	944
	.short	271
	.short	303
	.short	911
	.short	943
	.short	33668
	.short	33684
	.short	33700
	.short	33716
	.short	33732
	.short	33748
	.short	33764
	.short	33780
	.short	270
	.short	302
	.short	910
	.short	942
	.short	206
	.short	207
	.short	208
	.short	209
	.short	210
	.short	211
	.short	212
	.short	213
	.short	214
	.short	215
	.short	216
	.short	217
	.short	218
	.short	219
	.short	220
	.short	221
	.short	222
	.short	223
	.short	238
	.short	239
	.short	240
	.short	241
	.short	242
	.short	243
	.short	244
	.short	245
	.short	246
	.short	247
	.short	248
	.short	249
	.short	250
	.short	251
	.short	252
	.short	253
	.short	254
	.short	255
	.short	205
	.short	237
	.short	269
	.short	301
	.short	909
	.short	941
	.short	204
	.short	236
	.short	268
	.short	300
	.short	908
	.short	940
	.short	33667
	.short	33683
	.short	33699
	.short	33715
	.short	33731
	.short	33747
	.short	33763
	.short	33779
	.short	203
	.short	235
	.short	267
	.short	299
	.short	907
	.short	939
	.short	202
	.short	234
	.short	266
	.short	298
	.short	906
	.short	938
	.short	201
	.short	233
	.short	265
	.short	297
	.short	905
	.short	937
	.short	33666
	.short	33682
	.short	33698
	.short	33714
	.short	33730
	.short	33746
	.short	33762
	.short	33778
	.short	200
	.short	232
	.short	264
	.short	296
	.short	904
	.short	936
	.short	199
	.short	231
	.short	263
	.short	295
	.short	903
	.short	935
	.short	198
	.short	230
	.short	262
	.short	294
	.short	902
	.short	934
	.short	33665
	.short	33681
	.short	33697
	.short	33713
	.short	33729
	.short	33745
	.short	33761
	.short	33777
	.short	197
	.short	229
	.short	261
	.short	293
	.short	901
	.short	933
	.short	196
	.short	228
	.short	260
	.short	292
	.short	900
	.short	932
	.short	195
	.short	227
	.short	259
	.short	291
	.short	899
	.short	931
	.short	33664
	.short	33680
	.short	33696
	.short	33712
	.short	33728
	.short	33744
	.short	33760
	.short	33776
	.short	194
	.short	226
	.short	258
	.short	290
	.short	898
	.short	930
	.short	2
	.short	3
	.short	4
	.short	5
	.short	6
	.short	7
	.short	8
	.short	9
	.short	10
	.short	11
	.short	12
	.short	13
	.short	14
	.short	15
	.short	16
	.short	17
	.short	18
	.short	19
	.short	20
	.short	21
	.short	22
	.short	23
	.short	24
	.short	25
	.short	26
	.short	27
	.short	28
	.short	29
	.short	30
	.short	31
	.short	34
	.short	35
	.short	36
	.short	37
	.short	38
	.short	39
	.short	40
	.short	41
	.short	42
	.short	43
	.short	44
	.short	45
	.short	46
	.short	47
	.short	48
	.short	49
	.short	50
	.short	51
	.short	52
	.short	53
	.short	54
	.short	55
	.short	56
	.short	57
	.short	58
	.short	59
	.short	60
	.short	61
	.short	62
	.short	63
	.short	1
	.short	33
	.short	193
	.short	225
	.short	257
	.short	289
	.short	897
	.short	929
	.short	0
	.short	32
	.short	192
	.short	224
	.short	256
	.short	288
	.short	896
	.short	928
	.size	_ZL9ATT_ORDER, 6144

	.type	__hip_cuid_383b258efc50920b,@object
